# attention max chains: removed 206 compiler-inserted s_nop 0 pads after inline v_max3 (VALU to VALU, no hazard)
# speedup vs baseline: 1.0137x; 1.0137x over previous
; DI f32x16 mfma32(bf16x8 a, bf16x8 b, f32x16 c) { return __builtin_amdgcn_mfma_f32_32x32x16_bf16(a, b, c, 0, 0, 0); }
; template <int MODE>
; DI void attn_unit(char* lds, const Params& p, int layer, int u) {
;     ...
;     if (t + 1 < NT) { stage(lds + ((t + 1) & 1) * BUFSZ); if (t + 2 < NT) prefetch(t + 2); }
;     const int key0 = (MODE == 3) ? q0 - 64 + 64 * t : 64 * (tlo + t);
;     const bool act = (MODE != 3) || (t >= (wid >> 1) && t <= (wid >> 1) + 2);
;     if (act) {
;       f32x16 S0 = zero16(), S1 = zero16();
;       const char* kb = cur + lr * KST + (MODE == 0 ? comp * 64 : 0) + lh * 16;
; #pragma unroll
;       for (int ks = 0; ks < NKS; ++ks) {
;         const bf16x8 k0 = *(const bf16x8*)(kb + ks * 32), k1 = *(const bf16x8*)(kb + 32 * KST + ks * 32);
;         S0 = mfma32(k0, qf[ks], S0); S1 = mfma32(k1, qf[ks], S1);
;       }
;       float aoff = 0.f;
;       if (MODE == 0) {
;         const float dbase = (float)(key0 + 4 * lh - qrow);
;         if (key0 > qlo + 31) { S0 = S0 - T0; S1 = S1 - T1; aoff = -slope2 * dbase; }
;         else if (key0 + 63 < qlo) { S0 = S0 + T0; S1 = S1 + T1; aoff = slope2 * dbase; }
;         else {
; #pragma unroll
;           for (int r = 0; r < 16; ++r) { const float cc = (float)((r & 3) + 8 * (r >> 2));
;             S0[r] = fmaf(-slope2, fabsf(dbase + cc), S0[r]); S1[r] = fmaf(-slope2, fabsf(dbase + cc + 32.f), S1[r]); }
;         }
;       }
;       if (MODE == 3) {
;         const int rel0 = key0 + 4 * lh - qrow;
; #pragma unroll
;         for (int r = 0; r < 16; ++r) { const int cc = (r & 3) + 8 * (r >> 2);
;           { const int rel = rel0 + cc, v = qrow + rel; const bool ok = (rel >= -64) && (rel <= 64) && (v >= 0) && (v < L); S0[r] = ok ? fmaf(-slope2, fabsf((float)rel), S0[r]) : -1e30f; }
;           { const int rel = rel0 + cc + 32, v = qrow + rel; const bool ok = (rel >= -64) && (rel <= 64) && (v >= 0) && (v < L); S1[r] = ok ? fmaf(-slope2, fabsf((float)rel), S1[r]) : -1e30f; } }
;       }
;       float mx = fmaxf(S0[0], S1[0]);
; #pragma unroll
;       for (int r = 1; r < 16; ++r) mx = max3f(mx, S0[r], S1[r]);
;       mx += aoff;
;       if (__any(mx > m + 8.f)) {
;         mx = fmaxf(mx, __shfl_xor(mx, 32));
;         const float mnew = fmaxf(m, mx);
;         const float al = __builtin_amdgcn_exp2f(m - mnew); l *= al; O0 *= al; O1 *= al;
;         m = mnew;
;       }
.LBB0_586:
	s_bitcmp1_b32 s1, 0
	s_cselect_b32 s4, 0, 0x4800
	s_cselect_b32 s33, 0x4800, 0
	v_add_u32_e32 v32, s33, v94
	v_add_u32_e32 v102, s4, v100
	s_waitcnt vmcnt(1)
	ds_write_b128 v32, v[84:87]
	s_waitcnt vmcnt(0)
	ds_write_b128 v32, v[80:83] offset:9216
	v_add_u32_e32 v90, v102, v92
	ds_read_b128 v[32:35], v90
	ds_read_b128 v[104:107], v90 offset:32
	v_mad_i64_i32 v[80:81], s[50:51], v101, s72, v[96:97]
	ds_read_b128 v[48:51], v90 offset:4608
	global_load_dwordx4 v[84:87], v[80:81], off offset:3328
	s_nop 0
	global_load_dwordx4 v[80:83], v[98:99], off
	s_waitcnt lgkmcnt(2)
	v_mfma_f32_32x32x16_bf16 v[32:47], v[32:35], v[76:79], 0
	s_waitcnt lgkmcnt(1)
	v_mfma_f32_32x32x16_bf16 v[32:47], v[104:107], v[72:75], v[32:47]
	ds_read_b128 v[104:107], v90 offset:4640
	s_waitcnt lgkmcnt(1)
	v_mfma_f32_32x32x16_bf16 v[48:63], v[48:51], v[76:79], 0
	s_waitcnt lgkmcnt(0)
	v_mfma_f32_32x32x16_bf16 v[48:63], v[104:107], v[72:75], v[48:63]
	ds_read_b128 v[104:107], v90 offset:64
	s_waitcnt lgkmcnt(0)
	v_mfma_f32_32x32x16_bf16 v[32:47], v[104:107], v[68:71], v[32:47]
	ds_read_b128 v[104:107], v90 offset:4672
	s_waitcnt lgkmcnt(0)
	v_mfma_f32_32x32x16_bf16 v[48:63], v[104:107], v[68:71], v[48:63]
	ds_read_b128 v[104:107], v90 offset:4704
	s_waitcnt lgkmcnt(0)
	v_mfma_f32_32x32x16_bf16 v[48:63], v[104:107], v[64:67], v[48:63]
	ds_read_b128 v[104:107], v90 offset:96
	s_waitcnt lgkmcnt(0)
	v_mfma_f32_32x32x16_bf16 v[32:47], v[104:107], v[64:67], v[32:47]
	s_nop 8
	v_max_f32_e32 v90, v48, v48
	s_nop 1
	v_max_f32_e32 v91, v32, v32
	v_max_f32_e32 v90, v91, v90
	v_max3_f32 v90, v90, v33, v49
	v_add_f32_e32 v91, 0x41000000, v93
	v_max3_f32 v90, v90, v34, v50
	v_max3_f32 v90, v90, v35, v51
	v_max3_f32 v90, v90, v36, v52
	v_max3_f32 v90, v90, v37, v53
	v_max3_f32 v90, v90, v38, v54
	v_max3_f32 v90, v90, v39, v55
	v_max3_f32 v90, v90, v40, v56
	v_max3_f32 v90, v90, v41, v57
	v_max3_f32 v90, v90, v42, v58
	v_max3_f32 v90, v90, v43, v59
	v_max3_f32 v90, v90, v44, v60
	v_max3_f32 v90, v90, v45, v61
	v_max3_f32 v90, v90, v46, v62
	v_max3_f32 v90, v90, v47, v63
	v_cmp_gt_f32_e32 vcc, v90, v91
	s_cbranch_vccz .LBB0_585
	v_cmp_lt_i32_e32 vcc, v209, v208
	v_add_f32_e32 v90, 0, v90
	s_nop 0
	v_cndmask_b32_e32 v91, v207, v209, vcc
	v_lshlrev_b32_e32 v91, 2, v91
	ds_bpermute_b32 v91, v91, v90
	s_waitcnt lgkmcnt(0)
	v_max3_f32 v91, v93, v90, v91
	v_sub_f32_e32 v90, v93, v91
	v_exp_f32_e32 v90, v90
	v_mov_b32_e32 v93, v91
	v_mul_f32_e32 v95, v95, v90
	v_pk_mul_f32 v[14:15], v[14:15], v[90:91] op_sel_hi:[1,0]
	v_pk_mul_f32 v[12:13], v[12:13], v[90:91] op_sel_hi:[1,0]
	v_pk_mul_f32 v[10:11], v[10:11], v[90:91] op_sel_hi:[1,0]
	v_pk_mul_f32 v[8:9], v[8:9], v[90:91] op_sel_hi:[1,0]
	v_pk_mul_f32 v[6:7], v[6:7], v[90:91] op_sel_hi:[1,0]
	v_pk_mul_f32 v[4:5], v[4:5], v[90:91] op_sel_hi:[1,0]
	v_pk_mul_f32 v[2:3], v[2:3], v[90:91] op_sel_hi:[1,0]
	v_pk_mul_f32 v[0:1], v[0:1], v[90:91] op_sel_hi:[1,0]
	v_pk_mul_f32 v[30:31], v[30:31], v[90:91] op_sel_hi:[1,0]
	v_pk_mul_f32 v[28:29], v[28:29], v[90:91] op_sel_hi:[1,0]
	v_pk_mul_f32 v[26:27], v[26:27], v[90:91] op_sel_hi:[1,0]
	v_pk_mul_f32 v[24:25], v[24:25], v[90:91] op_sel_hi:[1,0]
	v_pk_mul_f32 v[22:23], v[22:23], v[90:91] op_sel_hi:[1,0]
	v_pk_mul_f32 v[20:21], v[20:21], v[90:91] op_sel_hi:[1,0]
	v_pk_mul_f32 v[18:19], v[18:19], v[90:91] op_sel_hi:[1,0]
	v_pk_mul_f32 v[16:17], v[16:17], v[90:91] op_sel_hi:[1,0]
	s_branch .LBB0_585
.LBB0_588:
	s_waitcnt vmcnt(1)
	ds_write_b128 v94, v[84:87] offset:18432
	s_waitcnt vmcnt(0)
	ds_write_b128 v94, v[80:83] offset:27648
	v_add_u32_e32 v82, v100, v92
	ds_read_b128 v[32:35], v82
	ds_read_b128 v[84:87], v82 offset:32
	ds_read_b128 v[48:51], v82 offset:4608
	v_add_f32_e32 v83, 0x41000000, v93
	s_waitcnt lgkmcnt(2)
	v_mfma_f32_32x32x16_bf16 v[32:47], v[32:35], v[76:79], 0
	s_waitcnt lgkmcnt(1)
	v_mfma_f32_32x32x16_bf16 v[32:47], v[84:87], v[72:75], v[32:47]
	ds_read_b128 v[84:87], v82 offset:4640
	s_waitcnt lgkmcnt(1)
	v_mfma_f32_32x32x16_bf16 v[48:63], v[48:51], v[76:79], 0
	s_waitcnt lgkmcnt(0)
	v_mfma_f32_32x32x16_bf16 v[48:63], v[84:87], v[72:75], v[48:63]
	ds_read_b128 v[84:87], v82 offset:64
	s_waitcnt lgkmcnt(0)
	v_mfma_f32_32x32x16_bf16 v[32:47], v[84:87], v[68:71], v[32:47]
	ds_read_b128 v[84:87], v82 offset:4672
	s_waitcnt lgkmcnt(0)
	v_mfma_f32_32x32x16_bf16 v[48:63], v[84:87], v[68:71], v[48:63]
	ds_read_b128 v[84:87], v82 offset:4704
	s_waitcnt lgkmcnt(0)
	v_mfma_f32_32x32x16_bf16 v[48:63], v[84:87], v[64:67], v[48:63]
	ds_read_b128 v[84:87], v82 offset:96
	s_waitcnt lgkmcnt(0)
	v_mfma_f32_32x32x16_bf16 v[32:47], v[84:87], v[64:67], v[32:47]
	s_nop 8
	v_max_f32_e32 v80, v48, v48
	s_nop 1
	v_max_f32_e32 v81, v32, v32
	v_max_f32_e32 v80, v81, v80
	v_max3_f32 v80, v80, v33, v49
	v_max3_f32 v80, v80, v34, v50
	v_max3_f32 v80, v80, v35, v51
	v_max3_f32 v80, v80, v36, v52
	v_max3_f32 v80, v80, v37, v53
	v_max3_f32 v80, v80, v38, v54
	v_max3_f32 v80, v80, v39, v55
	v_max3_f32 v80, v80, v40, v56
	v_max3_f32 v80, v80, v41, v57
	v_max3_f32 v80, v80, v42, v58
	v_max3_f32 v80, v80, v43, v59
	v_max3_f32 v80, v80, v44, v60
	v_max3_f32 v80, v80, v45, v61
	v_max3_f32 v80, v80, v46, v62
	v_max3_f32 v80, v80, v47, v63
	v_cmp_gt_f32_e32 vcc, v80, v83
	s_cbranch_vccz .LBB0_590
	v_cmp_lt_i32_e32 vcc, v209, v208
	v_add_f32_e32 v80, 0, v80
	s_nop 0
	v_cndmask_b32_e32 v81, v207, v209, vcc
	v_lshlrev_b32_e32 v81, 2, v81
	ds_bpermute_b32 v81, v81, v80
	s_waitcnt lgkmcnt(0)
	v_max3_f32 v81, v93, v80, v81
	v_sub_f32_e32 v80, v93, v81
	v_exp_f32_e32 v80, v80
	v_sub_f32_e32 v90, 0, v81
	v_add_f32_e32 v83, 0x41000000, v81
	v_mov_b32_e32 v93, v81
	v_mul_f32_e32 v95, v95, v80
	v_pk_mul_f32 v[14:15], v[14:15], v[80:81] op_sel_hi:[1,0]
	v_pk_mul_f32 v[12:13], v[12:13], v[80:81] op_sel_hi:[1,0]
	v_pk_mul_f32 v[10:11], v[10:11], v[80:81] op_sel_hi:[1,0]
	v_pk_mul_f32 v[8:9], v[8:9], v[80:81] op_sel_hi:[1,0]
	v_pk_mul_f32 v[6:7], v[6:7], v[80:81] op_sel_hi:[1,0]
	v_pk_mul_f32 v[4:5], v[4:5], v[80:81] op_sel_hi:[1,0]
	v_pk_mul_f32 v[2:3], v[2:3], v[80:81] op_sel_hi:[1,0]
	v_pk_mul_f32 v[0:1], v[0:1], v[80:81] op_sel_hi:[1,0]
	v_pk_mul_f32 v[30:31], v[30:31], v[80:81] op_sel_hi:[1,0]
	v_pk_mul_f32 v[28:29], v[28:29], v[80:81] op_sel_hi:[1,0]
	v_pk_mul_f32 v[26:27], v[26:27], v[80:81] op_sel_hi:[1,0]
	v_pk_mul_f32 v[24:25], v[24:25], v[80:81] op_sel_hi:[1,0]
	v_pk_mul_f32 v[22:23], v[22:23], v[80:81] op_sel_hi:[1,0]
	v_pk_mul_f32 v[20:21], v[20:21], v[80:81] op_sel_hi:[1,0]
	v_pk_mul_f32 v[18:19], v[18:19], v[80:81] op_sel_hi:[1,0]
	v_pk_mul_f32 v[16:17], v[16:17], v[80:81] op_sel_hi:[1,0]
; template <int MODE>
; DI void attn_unit(char* lds, const Params& p, int layer, int u) {
;     ...
;       f32x16 S0 = zero16(), S1 = zero16();
;       const char* kb = cur + lr * KST + (MODE == 0 ? comp * 64 : 0) + lh * 16;
; #pragma unroll
;       for (int ks = 0; ks < NKS; ++ks) {
;         const bf16x8 k0 = *(const bf16x8*)(kb + ks * 32), k1 = *(const bf16x8*)(kb + 32 * KST + ks * 32);
;         S0 = mfma32(k0, qf[ks], S0); S1 = mfma32(k1, qf[ks], S1);
;       }
;       float aoff = 0.f;
;       if (MODE == 0) {
;     ...
;       { const f32x2 nm = {aoff - m, aoff - m};
; #pragma unroll
;         for (int r = 0; r < 8; ++r) {
;           f32x2 a = {S0[2 * r], S0[2 * r + 1]}, b = {S1[2 * r], S1[2 * r + 1]};
;           asm("v_pk_add_f32 %0, %1, %2" : "=v"(a) : "v"(a), "v"(nm));
;           asm("v_pk_add_f32 %0, %1, %2" : "=v"(b) : "v"(b), "v"(nm));
;           S0[2 * r] = a[0]; S0[2 * r + 1] = a[1]; S1[2 * r] = b[0]; S1[2 * r + 1] = b[1];
;         } }
; #pragma unroll
;       for (int r = 0; r < 16; ++r) { S0[r] = __builtin_amdgcn_exp2f(S0[r]); S1[r] = __builtin_amdgcn_exp2f(S1[r]); }
;       const f32x16 SS = S0 + S1;
;       float ps = 0.f;
; #pragma unroll
;       for (int r = 0; r < 16; ++r) ps += SS[r];
;       l += ps;
;       bf16x8 pf[4];
; #pragma unroll
;       for (int s = 0; s < 4; ++s) {
;         u32x4 w;
;         if (s < 2) { w[0] = pk2(S0[8 * s], S0[8 * s + 1]); w[1] = pk2(S0[8 * s + 2], S0[8 * s + 3]); w[2] = pk2(S0[8 * s + 4], S0[8 * s + 5]); w[3] = pk2(S0[8 * s + 6], S0[8 * s + 7]); }
;         else { const int s2 = s - 2; w[0] = pk2(S1[8 * s2], S1[8 * s2 + 1]); w[1] = pk2(S1[8 * s2 + 2], S1[8 * s2 + 3]); w[2] = pk2(S1[8 * s2 + 4], S1[8 * s2 + 5]); w[3] = pk2(S1[8 * s2 + 6], S1[8 * s2 + 7]); }
;         pf[s] = __builtin_bit_cast(bf16x8, w);
;       }
;       const char* vb = cur + VOFF + lr * VST + lh * 8;
; #pragma unroll
;       for (int s = 0; s < 4; ++s) {
;         { const s16x4 lo = *(const s16x4*)(vb + s * 32), hi = *(const s16x4*)(vb + s * 32 + 16);
;           O0 = mfma32(__builtin_shufflevector(lo, hi, 0, 1, 2, 3, 4, 5, 6, 7), pf[s], O0); }
;         { const s16x4 lo = *(const s16x4*)(vb + 32 * VST + s * 32), hi = *(const s16x4*)(vb + 32 * VST + s * 32 + 16);
;           O1 = mfma32(__builtin_shufflevector(lo, hi, 0, 1, 2, 3, 4, 5, 6, 7), pf[s], O1); }
;       }
;     }
;     __syncthreads();
.LBB0_590:
	v_mov_b32_e32 v91, v90
	v_pk_add_f32 v[32:33], v[32:33], v[90:91]
	v_pk_add_f32 v[48:49], v[48:49], v[90:91]
	v_pk_add_f32 v[34:35], v[34:35], v[90:91]
	v_pk_add_f32 v[50:51], v[50:51], v[90:91]
	v_pk_add_f32 v[36:37], v[36:37], v[90:91]
	v_pk_add_f32 v[52:53], v[52:53], v[90:91]
	s_nop 0
	v_exp_f32_e32 v32, v32
	v_exp_f32_e32 v80, v48
	v_exp_f32_e32 v33, v33
	v_exp_f32_e32 v81, v49
	v_exp_f32_e32 v34, v34
	v_exp_f32_e32 v50, v50
	v_exp_f32_e32 v35, v35
	v_exp_f32_e32 v51, v51
	v_exp_f32_e32 v36, v36
	v_exp_f32_e32 v52, v52
	v_exp_f32_e32 v37, v37
	v_exp_f32_e32 v53, v53
	v_pk_add_f32 v[106:107], v[32:33], v[80:81]
	v_pk_add_f32 v[38:39], v[38:39], v[90:91]
	v_pk_add_f32 v[54:55], v[54:55], v[90:91]
	v_pk_add_f32 v[104:105], v[34:35], v[50:51]
	v_add_f32_e32 v92, 0, v106
	v_exp_f32_e32 v38, v38
	v_exp_f32_e32 v54, v54
	v_exp_f32_e32 v39, v39
	v_exp_f32_e32 v55, v55
	v_add_f32_e32 v92, v107, v92
	v_pk_add_f32 v[40:41], v[40:41], v[90:91]
	v_pk_add_f32 v[56:57], v[56:57], v[90:91]
	v_add_f32_e32 v92, v104, v92
	v_exp_f32_e32 v40, v40
	v_exp_f32_e32 v56, v56
	v_exp_f32_e32 v41, v41
	v_exp_f32_e32 v57, v57
	v_pk_add_f32 v[102:103], v[36:37], v[52:53]
	v_add_f32_e32 v92, v105, v92
	v_pk_add_f32 v[42:43], v[42:43], v[90:91]
	v_pk_add_f32 v[58:59], v[58:59], v[90:91]
	v_add_f32_e32 v92, v102, v92
	v_exp_f32_e32 v42, v42
	v_exp_f32_e32 v58, v58
	v_exp_f32_e32 v43, v43
	v_exp_f32_e32 v59, v59
	v_pk_add_f32 v[98:99], v[38:39], v[54:55]
	v_add_f32_e32 v92, v103, v92
	v_pk_add_f32 v[60:61], v[60:61], v[90:91]
	v_add_f32_e32 v92, v98, v92
	v_pk_add_f32 v[44:45], v[44:45], v[90:91]
	v_exp_f32_e32 v60, v60
	v_exp_f32_e32 v84, v44
	v_exp_f32_e32 v85, v45
	v_exp_f32_e32 v61, v61
	v_pk_add_f32 v[96:97], v[40:41], v[56:57]
	v_add_f32_e32 v92, v99, v92
	v_pk_add_f32 v[62:63], v[62:63], v[90:91]
	v_add_f32_e32 v92, v96, v92
	v_pk_add_f32 v[46:47], v[46:47], v[90:91]
	v_exp_f32_e32 v62, v62
	v_exp_f32_e32 v86, v46
	v_exp_f32_e32 v87, v47
	v_exp_f32_e32 v63, v63
	v_pk_add_f32 v[48:49], v[42:43], v[58:59]
	v_add_f32_e32 v92, v97, v92
	v_add_f32_e32 v48, v48, v92
	v_pk_add_f32 v[46:47], v[84:85], v[60:61]
	v_add_f32_e32 v48, v49, v48
	v_add_f32_e32 v46, v46, v48
	v_pk_add_f32 v[44:45], v[86:87], v[62:63]
	v_add_f32_e32 v46, v47, v46
	v_add_f32_e32 v44, v44, v46
	v_cvt_pk_bf16_f32 v46, v36, v37
	v_cvt_pk_bf16_f32 v36, v80, v81
	v_add_u32_e32 v80, v100, v112
	v_add_u32_e32 v49, 0x2000, v80
	v_add_f32_e32 v48, v45, v44
	v_cvt_pk_bf16_f32 v44, v32, v33
	v_cvt_pk_bf16_f32 v47, v38, v39
	v_cvt_pk_bf16_f32 v37, v50, v51
	v_cvt_pk_bf16_f32 v38, v52, v53
	v_cvt_pk_bf16_f32 v39, v54, v55
	v_cvt_pk_bf16_f32 v32, v56, v57
	ds_read2_b64 v[50:53], v49 offset0:128 offset1:130
	ds_read2_b64 v[54:57], v49 offset0:132 offset1:134
	v_cvt_pk_bf16_f32 v45, v34, v35
	v_cvt_pk_bf16_f32 v33, v58, v59
	v_add_u32_e32 v58, 0x3000, v80
	s_waitcnt lgkmcnt(1)
	v_mfma_f32_32x32x16_bf16 v[0:15], v[50:53], v[44:47], v[0:15]
	ds_read2_b64 v[50:53], v58 offset0:192 offset1:194
	v_cvt_pk_bf16_f32 v40, v40, v41
	v_cvt_pk_bf16_f32 v41, v42, v43
	v_cvt_pk_bf16_f32 v42, v84, v85
	v_cvt_pk_bf16_f32 v43, v86, v87
	v_cvt_pk_bf16_f32 v34, v60, v61
	v_cvt_pk_bf16_f32 v35, v62, v63
	s_waitcnt lgkmcnt(0)
	v_mfma_f32_32x32x16_bf16 v[16:31], v[50:53], v[44:47], v[16:31]
	ds_read2_b64 v[44:47], v58 offset0:196 offset1:198
	v_add_f32_e32 v81, v95, v48
	v_mfma_f32_32x32x16_bf16 v[0:15], v[54:57], v[40:43], v[0:15]
	s_waitcnt lgkmcnt(0)
	v_mfma_f32_32x32x16_bf16 v[16:31], v[44:47], v[40:43], v[16:31]
	ds_read2_b64 v[40:43], v49 offset0:136 offset1:138
	s_waitcnt lgkmcnt(0)
	v_mfma_f32_32x32x16_bf16 v[0:15], v[40:43], v[36:39], v[0:15]
	ds_read2_b64 v[40:43], v58 offset0:200 offset1:202
	s_waitcnt lgkmcnt(0)
	v_mfma_f32_32x32x16_bf16 v[16:31], v[40:43], v[36:39], v[16:31]
	ds_read2_b64 v[36:39], v49 offset0:140 offset1:142
	s_waitcnt lgkmcnt(0)
	v_mfma_f32_32x32x16_bf16 v[0:15], v[36:39], v[32:35], v[0:15]
	ds_read2_b64 v[36:39], v58 offset0:204 offset1:206
	s_waitcnt lgkmcnt(0)
	s_barrier
	v_mfma_f32_32x32x16_bf16 v[16:31], v[36:39], v[32:35], v[16:31]
	ds_read_b128 v[84:87], v82 offset:23136
	ds_read_b128 v[94:97], v82 offset:18528
	ds_read_b128 v[98:101], v82 offset:23104
	ds_read_b128 v[102:105], v82 offset:18496
	ds_read_b128 v[106:109], v82 offset:23072
	ds_read_b128 v[32:35], v82 offset:18432
	ds_read_b128 v[116:119], v82 offset:18464
	ds_read_b128 v[48:51], v82 offset:23040
	s_waitcnt lgkmcnt(2)
	v_mfma_f32_32x32x16_bf16 v[32:47], v[32:35], v[76:79], 0
	s_waitcnt lgkmcnt(0)
	v_mfma_f32_32x32x16_bf16 v[48:63], v[48:51], v[76:79], 0
	v_mfma_f32_32x32x16_bf16 v[32:47], v[116:119], v[72:75], v[32:47]
	v_mfma_f32_32x32x16_bf16 v[48:63], v[106:109], v[72:75], v[48:63]
	v_mfma_f32_32x32x16_bf16 v[32:47], v[102:105], v[68:71], v[32:47]
	v_mfma_f32_32x32x16_bf16 v[48:63], v[98:101], v[68:71], v[48:63]
	v_mfma_f32_32x32x16_bf16 v[32:47], v[94:97], v[64:67], v[32:47]
	v_mfma_f32_32x32x16_bf16 v[48:63], v[84:87], v[64:67], v[48:63]
	s_nop 10
	v_max_f32_e32 v65, v32, v32
	v_max_f32_e32 v64, v48, v48
	v_max_f32_e32 v64, v65, v64
	v_max3_f32 v64, v64, v33, v49
	v_max3_f32 v64, v64, v34, v50
	v_max3_f32 v64, v64, v35, v51
	v_max3_f32 v64, v64, v36, v52
	v_max3_f32 v64, v64, v37, v53
	v_max3_f32 v64, v64, v38, v54
	v_max3_f32 v64, v64, v39, v55
	v_max3_f32 v64, v64, v40, v56
	v_max3_f32 v64, v64, v41, v57
	v_max3_f32 v64, v64, v42, v58
	v_max3_f32 v64, v64, v43, v59
	v_max3_f32 v64, v64, v44, v60
	v_max3_f32 v64, v64, v45, v61
	v_max3_f32 v64, v64, v46, v62
	v_max3_f32 v64, v64, v47, v63
	v_cmp_gt_f32_e32 vcc, v64, v83
	s_cbranch_vccz .LBB0_592
	v_cmp_lt_i32_e32 vcc, v209, v208
	v_add_f32_e32 v64, 0, v64
	s_nop 0
	v_cndmask_b32_e32 v65, v207, v209, vcc
	v_lshlrev_b32_e32 v65, 2, v65
	ds_bpermute_b32 v65, v65, v64
	s_waitcnt lgkmcnt(0)
	v_max3_f32 v65, v93, v64, v65
	v_sub_f32_e32 v64, v93, v65
	v_exp_f32_e32 v64, v64
	v_sub_f32_e32 v90, 0, v65
	v_mov_b32_e32 v91, v90
	v_mul_f32_e32 v81, v81, v64
	v_pk_mul_f32 v[14:15], v[14:15], v[64:65] op_sel_hi:[1,0]
	v_pk_mul_f32 v[12:13], v[12:13], v[64:65] op_sel_hi:[1,0]
	v_pk_mul_f32 v[10:11], v[10:11], v[64:65] op_sel_hi:[1,0]
	v_pk_mul_f32 v[8:9], v[8:9], v[64:65] op_sel_hi:[1,0]
	v_pk_mul_f32 v[6:7], v[6:7], v[64:65] op_sel_hi:[1,0]
	v_pk_mul_f32 v[4:5], v[4:5], v[64:65] op_sel_hi:[1,0]
	v_pk_mul_f32 v[2:3], v[2:3], v[64:65] op_sel_hi:[1,0]
	v_pk_mul_f32 v[0:1], v[0:1], v[64:65] op_sel_hi:[1,0]
	v_pk_mul_f32 v[30:31], v[30:31], v[64:65] op_sel_hi:[1,0]
	v_pk_mul_f32 v[28:29], v[28:29], v[64:65] op_sel_hi:[1,0]
	v_pk_mul_f32 v[26:27], v[26:27], v[64:65] op_sel_hi:[1,0]
	v_pk_mul_f32 v[24:25], v[24:25], v[64:65] op_sel_hi:[1,0]
	v_pk_mul_f32 v[22:23], v[22:23], v[64:65] op_sel_hi:[1,0]
	v_pk_mul_f32 v[20:21], v[20:21], v[64:65] op_sel_hi:[1,0]
	v_pk_mul_f32 v[18:19], v[18:19], v[64:65] op_sel_hi:[1,0]
	v_pk_mul_f32 v[16:17], v[16:17], v[64:65] op_sel_hi:[1,0]

; DI f32x16 mfma32(bf16x8 a, bf16x8 b, f32x16 c) { return __builtin_amdgcn_mfma_f32_32x32x16_bf16(a, b, c, 0, 0, 0); }
; template <int MODE>
; DI void attn_unit(char* lds, const Params& p, int layer, int u) {
;     ...
;     if (t + 1 < NT) { stage(lds + ((t + 1) & 1) * BUFSZ); if (t + 2 < NT) prefetch(t + 2); }
;     const int key0 = (MODE == 3) ? q0 - 64 + 64 * t : 64 * (tlo + t);
;     const bool act = (MODE != 3) || (t >= (wid >> 1) && t <= (wid >> 1) + 2);
;     if (act) {
;       f32x16 S0 = zero16(), S1 = zero16();
;       const char* kb = cur + lr * KST + (MODE == 0 ? comp * 64 : 0) + lh * 16;
; #pragma unroll
;       for (int ks = 0; ks < NKS; ++ks) {
;         const bf16x8 k0 = *(const bf16x8*)(kb + ks * 32), k1 = *(const bf16x8*)(kb + 32 * KST + ks * 32);
;         S0 = mfma32(k0, qf[ks], S0); S1 = mfma32(k1, qf[ks], S1);
;       }
;       float aoff = 0.f;
;       if (MODE == 0) {
;         const float dbase = (float)(key0 + 4 * lh - qrow);
;         if (key0 > qlo + 31) { S0 = S0 - T0; S1 = S1 - T1; aoff = -slope2 * dbase; }
;         else if (key0 + 63 < qlo) { S0 = S0 + T0; S1 = S1 + T1; aoff = slope2 * dbase; }
;         else {
; #pragma unroll
;           for (int r = 0; r < 16; ++r) { const float cc = (float)((r & 3) + 8 * (r >> 2));
;             S0[r] = fmaf(-slope2, fabsf(dbase + cc), S0[r]); S1[r] = fmaf(-slope2, fabsf(dbase + cc + 32.f), S1[r]); }
;         }
;       }
;       if (MODE == 3) {
;         const int rel0 = key0 + 4 * lh - qrow;
; #pragma unroll
;         for (int r = 0; r < 16; ++r) { const int cc = (r & 3) + 8 * (r >> 2);
;           { const int rel = rel0 + cc, v = qrow + rel; const bool ok = (rel >= -64) && (rel <= 64) && (v >= 0) && (v < L); S0[r] = ok ? fmaf(-slope2, fabsf((float)rel), S0[r]) : -1e30f; }
;           { const int rel = rel0 + cc + 32, v = qrow + rel; const bool ok = (rel >= -64) && (rel <= 64) && (v >= 0) && (v < L); S1[r] = ok ? fmaf(-slope2, fabsf((float)rel), S1[r]) : -1e30f; } }
;       }
;       float mx = fmaxf(S0[0], S1[0]);
; #pragma unroll
;       for (int r = 1; r < 16; ++r) mx = max3f(mx, S0[r], S1[r]);
;       mx += aoff;
;       if (__any(mx > m + 8.f)) {
;         mx = fmaxf(mx, __shfl_xor(mx, 32));
;         const float mnew = fmaxf(m, mx);
;         const float al = __builtin_amdgcn_exp2f(m - mnew); l *= al; O0 *= al; O1 *= al;
;         m = mnew;
;       }
.LBB0_600:
	s_or_b64 exec, exec, s[66:67]
	s_cmp_eq_u32 s50, 1
	s_cselect_b32 s50, 0, 0x5800
	v_add3_u32 v32, s51, v123, v108
	s_waitcnt vmcnt(0)
	ds_write_b128 v32, v[92:95] offset:13312
	v_add3_u32 v104, s50, v103, v106
	ds_read_b128 v[32:35], v104
	ds_read_b128 v[88:91], v104 offset:32
	ds_read_b128 v[48:51], v104 offset:6656
	v_readlane_b32 s52, v252, 0
	v_readlane_b32 s60, v252, 8
	v_readlane_b32 s61, v252, 9
	v_readlane_b32 s53, v252, 1
	s_waitcnt lgkmcnt(2)
	v_mfma_f32_32x32x16_bf16 v[32:47], v[32:35], v[84:87], 0
	v_mov_b64_e32 v[92:93], s[60:61]
	v_mad_i64_i32 v[92:93], s[52:53], v116, s72, v[92:93]
	v_ashrrev_i32_e32 v117, 31, v116
	v_lshl_add_u64 v[92:93], v[92:93], 0, v[112:113]
	v_add_co_u32_e32 v92, vcc, s74, v92
	s_waitcnt lgkmcnt(1)
	v_mfma_f32_32x32x16_bf16 v[32:47], v[88:91], v[80:83], v[32:47]
	ds_read_b128 v[88:91], v104 offset:6688
	v_addc_co_u32_e32 v93, vcc, 0, v93, vcc
	v_readlane_b32 s54, v252, 2
	v_readlane_b32 s55, v252, 3
	v_readlane_b32 s56, v252, 4
	v_readlane_b32 s57, v252, 5
	s_waitcnt lgkmcnt(1)
	v_mfma_f32_32x32x16_bf16 v[48:63], v[48:51], v[84:87], 0
	v_readlane_b32 s58, v252, 6
	v_readlane_b32 s59, v252, 7
	v_readlane_b32 s62, v252, 10
	v_readlane_b32 s63, v252, 11
	v_readlane_b32 s64, v252, 12
	v_readlane_b32 s65, v252, 13
	v_readlane_b32 s66, v252, 14
	s_waitcnt lgkmcnt(0)
	v_mfma_f32_32x32x16_bf16 v[48:63], v[88:91], v[80:83], v[48:63]
	ds_read_b128 v[88:91], v104 offset:64
	v_readlane_b32 s67, v252, 15
	s_waitcnt lgkmcnt(0)
	v_mfma_f32_32x32x16_bf16 v[32:47], v[88:91], v[76:79], v[32:47]
	ds_read_b128 v[88:91], v104 offset:6720
	ds_read_b128 v[126:129], v104 offset:96
	s_waitcnt lgkmcnt(1)
	v_mfma_f32_32x32x16_bf16 v[48:63], v[88:91], v[76:79], v[48:63]
	v_lshlrev_b64 v[88:89], 9, v[116:117]
	v_lshl_add_u64 v[88:89], v[110:111], 0, v[88:89]
	global_load_dwordx4 v[88:91], v[88:89], off
	s_nop 0
	global_load_dwordx4 v[96:99], v[92:93], off offset:1280
	s_nop 0
	global_load_dwordx4 v[92:95], v[118:119], off
	s_waitcnt lgkmcnt(0)
	v_mfma_f32_32x32x16_bf16 v[32:47], v[126:129], v[72:75], v[32:47]
	ds_read_b128 v[126:129], v104 offset:6752
	s_waitcnt lgkmcnt(0)
	v_mfma_f32_32x32x16_bf16 v[48:63], v[126:129], v[72:75], v[48:63]
	ds_read_b128 v[126:129], v104 offset:128
	s_waitcnt lgkmcnt(0)
	v_mfma_f32_32x32x16_bf16 v[32:47], v[126:129], v[68:71], v[32:47]
	ds_read_b128 v[126:129], v104 offset:6784
	s_waitcnt lgkmcnt(0)
	v_mfma_f32_32x32x16_bf16 v[48:63], v[126:129], v[68:71], v[48:63]
	ds_read_b128 v[126:129], v104 offset:6816
	s_waitcnt lgkmcnt(0)
	v_mfma_f32_32x32x16_bf16 v[48:63], v[126:129], v[64:67], v[48:63]
	ds_read_b128 v[126:129], v104 offset:160
	s_waitcnt lgkmcnt(0)
	v_mfma_f32_32x32x16_bf16 v[32:47], v[126:129], v[64:67], v[32:47]
	s_nop 8
	v_max_f32_e32 v104, v48, v48
	s_nop 1
	v_max_f32_e32 v105, v32, v32
	v_max_f32_e32 v104, v105, v104
	v_max3_f32 v104, v104, v33, v49
	v_add_f32_e32 v105, 0x41000000, v107
	v_max3_f32 v104, v104, v34, v50
	v_max3_f32 v104, v104, v35, v51
	v_max3_f32 v104, v104, v36, v52
	v_max3_f32 v104, v104, v37, v53
	v_max3_f32 v104, v104, v38, v54
	v_max3_f32 v104, v104, v39, v55
	v_max3_f32 v104, v104, v40, v56
	v_max3_f32 v104, v104, v41, v57
	v_max3_f32 v104, v104, v42, v58
	v_max3_f32 v104, v104, v43, v59
	v_max3_f32 v104, v104, v44, v60
	v_max3_f32 v104, v104, v45, v61
	v_max3_f32 v104, v104, v46, v62
	v_max3_f32 v104, v104, v47, v63
	v_cmp_gt_f32_e32 vcc, v104, v105
	s_cbranch_vccz .LBB0_597
	v_cmp_lt_i32_e32 vcc, v209, v208
	v_add_f32_e32 v104, 0, v104
	s_nop 0
	v_cndmask_b32_e32 v105, v207, v209, vcc
	v_lshlrev_b32_e32 v105, 2, v105
	ds_bpermute_b32 v105, v105, v104
	s_waitcnt lgkmcnt(0)
	v_max3_f32 v105, v107, v104, v105
	v_sub_f32_e32 v104, v107, v105
	v_exp_f32_e32 v104, v104
	v_mov_b32_e32 v107, v105
	v_mul_f32_e32 v109, v109, v104
	v_pk_mul_f32 v[14:15], v[14:15], v[104:105] op_sel_hi:[1,0]
	v_pk_mul_f32 v[12:13], v[12:13], v[104:105] op_sel_hi:[1,0]
	v_pk_mul_f32 v[10:11], v[10:11], v[104:105] op_sel_hi:[1,0]
	v_pk_mul_f32 v[8:9], v[8:9], v[104:105] op_sel_hi:[1,0]
	v_pk_mul_f32 v[6:7], v[6:7], v[104:105] op_sel_hi:[1,0]
	v_pk_mul_f32 v[4:5], v[4:5], v[104:105] op_sel_hi:[1,0]
	v_pk_mul_f32 v[2:3], v[2:3], v[104:105] op_sel_hi:[1,0]
	v_pk_mul_f32 v[0:1], v[0:1], v[104:105] op_sel_hi:[1,0]
	v_pk_mul_f32 v[30:31], v[30:31], v[104:105] op_sel_hi:[1,0]
	v_pk_mul_f32 v[28:29], v[28:29], v[104:105] op_sel_hi:[1,0]
	v_pk_mul_f32 v[26:27], v[26:27], v[104:105] op_sel_hi:[1,0]
	v_pk_mul_f32 v[24:25], v[24:25], v[104:105] op_sel_hi:[1,0]
	v_pk_mul_f32 v[22:23], v[22:23], v[104:105] op_sel_hi:[1,0]
	v_pk_mul_f32 v[20:21], v[20:21], v[104:105] op_sel_hi:[1,0]
	v_pk_mul_f32 v[18:19], v[18:19], v[104:105] op_sel_hi:[1,0]
	v_pk_mul_f32 v[16:17], v[16:17], v[104:105] op_sel_hi:[1,0]
	s_branch .LBB0_597

; DI float max3f(float a, float b, float c) { float d; asm("v_max3_f32 %0, %1, %2, %3" : "=v"(d) : "v"(a), "v"(b), "v"(c)); return d; }
; template <int MODE>
; DI void attn_unit(char* lds, const Params& p, int layer, int u) {
;     ...
;       float mx = fmaxf(S0[0], S1[0]);
; #pragma unroll
;       for (int r = 1; r < 16; ++r) mx = max3f(mx, S0[r], S1[r]);
;       mx += aoff;
;       if (__any(mx > m + 8.f)) {
;         mx = fmaxf(mx, __shfl_xor(mx, 32));
;         const float mnew = fmaxf(m, mx);
;         const float al = __builtin_amdgcn_exp2f(m - mnew); l *= al; O0 *= al; O1 *= al;
;         m = mnew;
;       }
.LBB0_632:
	s_or_b64 exec, exec, s[68:69]
	s_nop 3
	v_max_f32_e32 v64, v48, v48
	v_max_f32_e32 v65, v32, v32
	v_max_f32_e32 v64, v65, v64
	v_max3_f32 v64, v64, v33, v49
	v_max3_f32 v64, v64, v34, v50
	v_max3_f32 v64, v64, v35, v51
	v_max3_f32 v64, v64, v36, v52
	v_max3_f32 v64, v64, v37, v53
	v_max3_f32 v64, v64, v38, v54
	v_max3_f32 v64, v64, v39, v55
	v_max3_f32 v64, v64, v40, v56
	v_max3_f32 v64, v64, v41, v57
	v_max3_f32 v64, v64, v42, v58
	v_max3_f32 v64, v64, v43, v59
	v_max3_f32 v64, v64, v44, v60
	v_max3_f32 v64, v64, v45, v61
	v_max3_f32 v64, v64, v46, v62
	v_max3_f32 v114, v64, v47, v63
	v_pk_add_f32 v[64:65], v[162:163], v[114:115]
	s_nop 0
	v_cmp_gt_f32_e32 vcc, v64, v65
	s_cbranch_vccz .LBB0_634
	v_cmp_lt_i32_e32 vcc, v209, v208
	s_nop 1
	v_cndmask_b32_e32 v65, v207, v209, vcc
	v_lshlrev_b32_e32 v65, 2, v65
	ds_bpermute_b32 v65, v65, v64
	s_waitcnt lgkmcnt(0)
	v_max3_f32 v65, v163, v64, v65
	v_sub_f32_e32 v64, v163, v65
	v_exp_f32_e32 v64, v64
	v_mov_b32_e32 v163, v65
	v_mul_f32_e32 v121, v121, v64
	v_pk_mul_f32 v[14:15], v[14:15], v[64:65] op_sel_hi:[1,0]
	v_pk_mul_f32 v[12:13], v[12:13], v[64:65] op_sel_hi:[1,0]
	v_pk_mul_f32 v[10:11], v[10:11], v[64:65] op_sel_hi:[1,0]
	v_pk_mul_f32 v[8:9], v[8:9], v[64:65] op_sel_hi:[1,0]
	v_pk_mul_f32 v[6:7], v[6:7], v[64:65] op_sel_hi:[1,0]
	v_pk_mul_f32 v[4:5], v[4:5], v[64:65] op_sel_hi:[1,0]
	v_pk_mul_f32 v[2:3], v[2:3], v[64:65] op_sel_hi:[1,0]
	v_pk_mul_f32 v[0:1], v[0:1], v[64:65] op_sel_hi:[1,0]
	v_pk_mul_f32 v[30:31], v[30:31], v[64:65] op_sel_hi:[1,0]
	v_pk_mul_f32 v[28:29], v[28:29], v[64:65] op_sel_hi:[1,0]
	v_pk_mul_f32 v[26:27], v[26:27], v[64:65] op_sel_hi:[1,0]
	v_pk_mul_f32 v[24:25], v[24:25], v[64:65] op_sel_hi:[1,0]
	v_pk_mul_f32 v[22:23], v[22:23], v[64:65] op_sel_hi:[1,0]
	v_pk_mul_f32 v[20:21], v[20:21], v[64:65] op_sel_hi:[1,0]
	v_pk_mul_f32 v[18:19], v[18:19], v[64:65] op_sel_hi:[1,0]
	v_pk_mul_f32 v[16:17], v[16:17], v[64:65] op_sel_hi:[1,0]

; template <int MODE>
; DI void attn_unit(char* lds, const Params& p, int layer, int u) {
;     ...
;       f32x16 S0 = zero16(), S1 = zero16();
;       const char* kb = cur + lr * KST + (MODE == 0 ? comp * 64 : 0) + lh * 16;
; #pragma unroll
;       for (int ks = 0; ks < NKS; ++ks) {
;         const bf16x8 k0 = *(const bf16x8*)(kb + ks * 32), k1 = *(const bf16x8*)(kb + 32 * KST + ks * 32);
;         S0 = mfma32(k0, qf[ks], S0); S1 = mfma32(k1, qf[ks], S1);
;       }
;       float aoff = 0.f;
;       if (MODE == 0) {
;         const float dbase = (float)(key0 + 4 * lh - qrow);
;         if (key0 > qlo + 31) { S0 = S0 - T0; S1 = S1 - T1; aoff = -slope2 * dbase; }
;         else if (key0 + 63 < qlo) { S0 = S0 + T0; S1 = S1 + T1; aoff = slope2 * dbase; }
;         else {
; #pragma unroll
;           for (int r = 0; r < 16; ++r) { const float cc = (float)((r & 3) + 8 * (r >> 2));
;             S0[r] = fmaf(-slope2, fabsf(dbase + cc), S0[r]); S1[r] = fmaf(-slope2, fabsf(dbase + cc + 32.f), S1[r]); }
;         }
;       }
;       if (MODE == 3) {
;         const int rel0 = key0 + 4 * lh - qrow;
; #pragma unroll
;         for (int r = 0; r < 16; ++r) { const int cc = (r & 3) + 8 * (r >> 2);
;           { const int rel = rel0 + cc, v = qrow + rel; const bool ok = (rel >= -64) && (rel <= 64) && (v >= 0) && (v < L); S0[r] = ok ? fmaf(-slope2, fabsf((float)rel), S0[r]) : -1e30f; }
;           { const int rel = rel0 + cc + 32, v = qrow + rel; const bool ok = (rel >= -64) && (rel <= 64) && (v >= 0) && (v < L); S1[r] = ok ? fmaf(-slope2, fabsf((float)rel), S1[r]) : -1e30f; } }
;       }
;       float mx = fmaxf(S0[0], S1[0]);
; #pragma unroll
;       for (int r = 1; r < 16; ++r) mx = max3f(mx, S0[r], S1[r]);
;       mx += aoff;
;       if (__any(mx > m + 8.f)) {
;         mx = fmaxf(mx, __shfl_xor(mx, 32));
;         const float mnew = fmaxf(m, mx);
;         const float al = __builtin_amdgcn_exp2f(m - mnew); l *= al; O0 *= al; O1 *= al;
;         m = mnew;
;       }
;       { const f32x2 nm = {aoff - m, aoff - m};
; #pragma unroll
;         for (int r = 0; r < 8; ++r) {
;           f32x2 a = {S0[2 * r], S0[2 * r + 1]}, b = {S1[2 * r], S1[2 * r + 1]};
;           asm("v_pk_add_f32 %0, %1, %2" : "=v"(a) : "v"(a), "v"(nm));
;           asm("v_pk_add_f32 %0, %1, %2" : "=v"(b) : "v"(b), "v"(nm));
.LBB0_646:
	s_or_b64 exec, exec, s[66:67]
	s_waitcnt vmcnt(0)
	ds_write_b128 v122, v[92:95] offset:35840
	v_add_u32_e32 v94, v103, v106
	ds_read_b128 v[32:35], v94
	ds_read_b128 v[88:91], v94 offset:32
	ds_read_b128 v[48:51], v94 offset:6656
	v_add_f32_e32 v93, 0x41000000, v107
	s_waitcnt lgkmcnt(2)
	v_mfma_f32_32x32x16_bf16 v[32:47], v[32:35], v[84:87], 0
	s_waitcnt lgkmcnt(1)
	v_mfma_f32_32x32x16_bf16 v[32:47], v[88:91], v[80:83], v[32:47]
	ds_read_b128 v[88:91], v94 offset:6688
	s_waitcnt lgkmcnt(1)
	v_mfma_f32_32x32x16_bf16 v[48:63], v[48:51], v[84:87], 0
	s_waitcnt lgkmcnt(0)
	v_mfma_f32_32x32x16_bf16 v[48:63], v[88:91], v[80:83], v[48:63]
	ds_read_b128 v[88:91], v94 offset:64
	s_waitcnt lgkmcnt(0)
	v_mfma_f32_32x32x16_bf16 v[32:47], v[88:91], v[76:79], v[32:47]
	ds_read_b128 v[88:91], v94 offset:6720
	s_waitcnt lgkmcnt(0)
	v_mfma_f32_32x32x16_bf16 v[48:63], v[88:91], v[76:79], v[48:63]
	ds_read_b128 v[88:91], v94 offset:96
	s_waitcnt lgkmcnt(0)
	v_mfma_f32_32x32x16_bf16 v[32:47], v[88:91], v[72:75], v[32:47]
	ds_read_b128 v[88:91], v94 offset:6752
	s_waitcnt lgkmcnt(0)
	v_mfma_f32_32x32x16_bf16 v[48:63], v[88:91], v[72:75], v[48:63]
	ds_read_b128 v[88:91], v94 offset:128
	s_waitcnt lgkmcnt(0)
	v_mfma_f32_32x32x16_bf16 v[32:47], v[88:91], v[68:71], v[32:47]
	ds_read_b128 v[88:91], v94 offset:6784
	s_waitcnt lgkmcnt(0)
	v_mfma_f32_32x32x16_bf16 v[48:63], v[88:91], v[68:71], v[48:63]
	ds_read_b128 v[88:91], v94 offset:6816
	s_waitcnt lgkmcnt(0)
	v_mfma_f32_32x32x16_bf16 v[48:63], v[88:91], v[64:67], v[48:63]
	ds_read_b128 v[88:91], v94 offset:160
	s_waitcnt lgkmcnt(0)
	v_mfma_f32_32x32x16_bf16 v[32:47], v[88:91], v[64:67], v[32:47]
	s_nop 8
	v_max_f32_e32 v92, v48, v48
	s_nop 1
	v_max_f32_e32 v88, v32, v32
	v_max_f32_e32 v88, v88, v92
	v_max3_f32 v88, v88, v33, v49
	v_max3_f32 v88, v88, v34, v50
	v_max3_f32 v88, v88, v35, v51
	v_max3_f32 v88, v88, v36, v52
	v_max3_f32 v88, v88, v37, v53
	v_max3_f32 v88, v88, v38, v54
	v_max3_f32 v88, v88, v39, v55
	v_max3_f32 v88, v88, v40, v56
	v_max3_f32 v88, v88, v41, v57
	v_max3_f32 v88, v88, v42, v58
	v_max3_f32 v88, v88, v43, v59
	v_max3_f32 v88, v88, v44, v60
	v_max3_f32 v88, v88, v45, v61
	v_max3_f32 v88, v88, v46, v62
	v_max3_f32 v88, v88, v47, v63
	v_cmp_gt_f32_e32 vcc, v88, v93
	s_cbranch_vccz .LBB0_648
	v_cmp_lt_i32_e32 vcc, v209, v208
	v_add_f32_e32 v88, 0, v88
	s_nop 0
	v_cndmask_b32_e32 v89, v207, v209, vcc
	v_lshlrev_b32_e32 v89, 2, v89
	ds_bpermute_b32 v89, v89, v88
	s_waitcnt lgkmcnt(0)
	v_max3_f32 v89, v107, v88, v89
	v_sub_f32_e32 v88, v107, v89
	v_exp_f32_e32 v88, v88
	v_sub_f32_e32 v104, 0, v89
	v_add_f32_e32 v93, 0x41000000, v89
	v_mov_b32_e32 v107, v89
	v_mul_f32_e32 v109, v109, v88
	v_pk_mul_f32 v[14:15], v[14:15], v[88:89] op_sel_hi:[1,0]
	v_pk_mul_f32 v[12:13], v[12:13], v[88:89] op_sel_hi:[1,0]
	v_pk_mul_f32 v[10:11], v[10:11], v[88:89] op_sel_hi:[1,0]
	v_pk_mul_f32 v[8:9], v[8:9], v[88:89] op_sel_hi:[1,0]
	v_pk_mul_f32 v[6:7], v[6:7], v[88:89] op_sel_hi:[1,0]
	v_pk_mul_f32 v[4:5], v[4:5], v[88:89] op_sel_hi:[1,0]
	v_pk_mul_f32 v[2:3], v[2:3], v[88:89] op_sel_hi:[1,0]
	v_pk_mul_f32 v[0:1], v[0:1], v[88:89] op_sel_hi:[1,0]
	v_pk_mul_f32 v[30:31], v[30:31], v[88:89] op_sel_hi:[1,0]
	v_pk_mul_f32 v[28:29], v[28:29], v[88:89] op_sel_hi:[1,0]
	v_pk_mul_f32 v[26:27], v[26:27], v[88:89] op_sel_hi:[1,0]
	v_pk_mul_f32 v[24:25], v[24:25], v[88:89] op_sel_hi:[1,0]
	v_pk_mul_f32 v[22:23], v[22:23], v[88:89] op_sel_hi:[1,0]
	v_pk_mul_f32 v[20:21], v[20:21], v[88:89] op_sel_hi:[1,0]
	v_pk_mul_f32 v[18:19], v[18:19], v[88:89] op_sel_hi:[1,0]
	v_pk_mul_f32 v[16:17], v[16:17], v[88:89] op_sel_hi:[1,0]
.LBB0_648:
	v_mov_b32_e32 v105, v104
	v_pk_add_f32 v[32:33], v[32:33], v[104:105]
	v_pk_add_f32 v[48:49], v[48:49], v[104:105]
	v_pk_add_f32 v[34:35], v[34:35], v[104:105]
	v_pk_add_f32 v[50:51], v[50:51], v[104:105]
	v_pk_add_f32 v[36:37], v[36:37], v[104:105]
	v_pk_add_f32 v[52:53], v[52:53], v[104:105]
	s_nop 0
	v_exp_f32_e32 v32, v32
	v_exp_f32_e32 v88, v48
	v_exp_f32_e32 v33, v33
	v_exp_f32_e32 v89, v49
	v_exp_f32_e32 v34, v34
	v_exp_f32_e32 v50, v50
	v_exp_f32_e32 v35, v35
	v_exp_f32_e32 v51, v51
	v_exp_f32_e32 v36, v36
	v_exp_f32_e32 v52, v52
	v_exp_f32_e32 v37, v37
	v_exp_f32_e32 v53, v53
	v_pk_add_f32 v[120:121], v[32:33], v[88:89]
	v_pk_add_f32 v[38:39], v[38:39], v[104:105]
	v_pk_add_f32 v[54:55], v[54:55], v[104:105]
	v_pk_add_f32 v[118:119], v[34:35], v[50:51]
	v_add_f32_e32 v92, 0, v120
	v_exp_f32_e32 v38, v38
	v_exp_f32_e32 v54, v54
	v_exp_f32_e32 v39, v39
	v_exp_f32_e32 v55, v55
	v_add_f32_e32 v92, v121, v92
	v_pk_add_f32 v[40:41], v[40:41], v[104:105]
	v_pk_add_f32 v[56:57], v[56:57], v[104:105]
	v_add_f32_e32 v92, v118, v92
	v_exp_f32_e32 v40, v40
	v_exp_f32_e32 v56, v56
	v_exp_f32_e32 v41, v41
	v_exp_f32_e32 v57, v57
	v_pk_add_f32 v[116:117], v[36:37], v[52:53]
	v_add_f32_e32 v92, v119, v92
	v_pk_add_f32 v[42:43], v[42:43], v[104:105]
	v_pk_add_f32 v[58:59], v[58:59], v[104:105]
	v_add_f32_e32 v92, v116, v92
	v_exp_f32_e32 v42, v42
	v_exp_f32_e32 v58, v58
	v_exp_f32_e32 v43, v43
	v_exp_f32_e32 v59, v59
	v_pk_add_f32 v[110:111], v[38:39], v[54:55]
	v_add_f32_e32 v92, v117, v92
	v_pk_add_f32 v[60:61], v[60:61], v[104:105]
	v_add_f32_e32 v92, v110, v92
	v_pk_add_f32 v[44:45], v[44:45], v[104:105]
	v_exp_f32_e32 v60, v60
	v_exp_f32_e32 v90, v44
	v_exp_f32_e32 v91, v45
	v_exp_f32_e32 v61, v61
	v_pk_add_f32 v[98:99], v[40:41], v[56:57]
	v_add_f32_e32 v92, v111, v92
	v_pk_add_f32 v[62:63], v[62:63], v[104:105]
	v_add_f32_e32 v92, v98, v92
	v_pk_add_f32 v[46:47], v[46:47], v[104:105]
	v_exp_f32_e32 v62, v62
	v_exp_f32_e32 v96, v46
	v_exp_f32_e32 v97, v47
	v_exp_f32_e32 v63, v63
	v_pk_add_f32 v[48:49], v[42:43], v[58:59]
	v_add_f32_e32 v92, v99, v92
	v_add_f32_e32 v48, v48, v92
	v_pk_add_f32 v[46:47], v[90:91], v[60:61]
	v_add_f32_e32 v48, v49, v48
	v_add_f32_e32 v46, v46, v48
	v_lshlrev_b32_e32 v95, 6, v114
	v_pk_add_f32 v[44:45], v[96:97], v[62:63]
	v_add_f32_e32 v46, v47, v46
	v_sub_u32_e32 v49, v103, v95
	v_add_f32_e32 v44, v44, v46
	v_add_u32_e32 v49, v49, v102
	v_add_f32_e32 v48, v45, v44
	v_cvt_pk_bf16_f32 v44, v32, v33
	v_cvt_pk_bf16_f32 v33, v58, v59
	v_add_u32_e32 v58, 0x3000, v49
	v_cvt_pk_bf16_f32 v46, v36, v37
	v_cvt_pk_bf16_f32 v47, v38, v39
	v_cvt_pk_bf16_f32 v37, v50, v51
	v_cvt_pk_bf16_f32 v38, v52, v53
	v_cvt_pk_bf16_f32 v39, v54, v55
	v_cvt_pk_bf16_f32 v32, v56, v57
	ds_read2_b64 v[50:53], v58 offset0:128 offset1:130
	ds_read2_b64 v[54:57], v58 offset0:132 offset1:134
	v_cvt_pk_bf16_f32 v45, v34, v35
	v_add_u32_e32 v49, 0x4000, v49
	v_cvt_pk_bf16_f32 v40, v40, v41
	s_waitcnt lgkmcnt(1)
; template <int MODE>
; DI void attn_unit(char* lds, const Params& p, int layer, int u) {
;     ...
;       f32x16 S0 = zero16(), S1 = zero16();
;       const char* kb = cur + lr * KST + (MODE == 0 ? comp * 64 : 0) + lh * 16;
; #pragma unroll
;       for (int ks = 0; ks < NKS; ++ks) {
;         const bf16x8 k0 = *(const bf16x8*)(kb + ks * 32), k1 = *(const bf16x8*)(kb + 32 * KST + ks * 32);
;         S0 = mfma32(k0, qf[ks], S0); S1 = mfma32(k1, qf[ks], S1);
;       }
;       float aoff = 0.f;
;       if (MODE == 0) {
;         const float dbase = (float)(key0 + 4 * lh - qrow);
;         if (key0 > qlo + 31) { S0 = S0 - T0; S1 = S1 - T1; aoff = -slope2 * dbase; }
;         else if (key0 + 63 < qlo) { S0 = S0 + T0; S1 = S1 + T1; aoff = slope2 * dbase; }
;         else {
; #pragma unroll
;           for (int r = 0; r < 16; ++r) { const float cc = (float)((r & 3) + 8 * (r >> 2));
;             S0[r] = fmaf(-slope2, fabsf(dbase + cc), S0[r]); S1[r] = fmaf(-slope2, fabsf(dbase + cc + 32.f), S1[r]); }
;         }
;       }
;       if (MODE == 3) {
;         const int rel0 = key0 + 4 * lh - qrow;
; #pragma unroll
;         for (int r = 0; r < 16; ++r) { const int cc = (r & 3) + 8 * (r >> 2);
;           { const int rel = rel0 + cc, v = qrow + rel; const bool ok = (rel >= -64) && (rel <= 64) && (v >= 0) && (v < L); S0[r] = ok ? fmaf(-slope2, fabsf((float)rel), S0[r]) : -1e30f; }
;           { const int rel = rel0 + cc + 32, v = qrow + rel; const bool ok = (rel >= -64) && (rel <= 64) && (v >= 0) && (v < L); S1[r] = ok ? fmaf(-slope2, fabsf((float)rel), S1[r]) : -1e30f; } }
;       }
;       float mx = fmaxf(S0[0], S1[0]);
; #pragma unroll
;       for (int r = 1; r < 16; ++r) mx = max3f(mx, S0[r], S1[r]);
;       mx += aoff;
;       if (__any(mx > m + 8.f)) {
;         mx = fmaxf(mx, __shfl_xor(mx, 32));
;     ...
;       const char* vb = cur + VOFF + lr * VST + lh * 8;
; #pragma unroll
;       for (int s = 0; s < 4; ++s) {
;         { const s16x4 lo = *(const s16x4*)(vb + s * 32), hi = *(const s16x4*)(vb + s * 32 + 16);
;           O0 = mfma32(__builtin_shufflevector(lo, hi, 0, 1, 2, 3, 4, 5, 6, 7), pf[s], O0); }
;         { const s16x4 lo = *(const s16x4*)(vb + 32 * VST + s * 32), hi = *(const s16x4*)(vb + 32 * VST + s * 32 + 16);
;           O1 = mfma32(__builtin_shufflevector(lo, hi, 0, 1, 2, 3, 4, 5, 6, 7), pf[s], O1); }
;       }
;     }
;     __syncthreads();
	v_mfma_f32_32x32x16_bf16 v[0:15], v[50:53], v[44:47], v[0:15]
	ds_read2_b64 v[50:53], v49 offset0:192 offset1:194
	v_cvt_pk_bf16_f32 v41, v42, v43
	v_cvt_pk_bf16_f32 v42, v90, v91
	v_cvt_pk_bf16_f32 v43, v96, v97
	v_cvt_pk_bf16_f32 v36, v88, v89
	v_cvt_pk_bf16_f32 v34, v60, v61
	v_cvt_pk_bf16_f32 v35, v62, v63
	s_waitcnt lgkmcnt(0)
	v_mfma_f32_32x32x16_bf16 v[16:31], v[50:53], v[44:47], v[16:31]
	ds_read2_b64 v[44:47], v49 offset0:196 offset1:198
	v_add_f32_e32 v92, v109, v48
	v_mfma_f32_32x32x16_bf16 v[0:15], v[54:57], v[40:43], v[0:15]
	s_waitcnt lgkmcnt(0)
	v_mfma_f32_32x32x16_bf16 v[16:31], v[44:47], v[40:43], v[16:31]
	ds_read2_b64 v[40:43], v58 offset0:136 offset1:138
	s_waitcnt lgkmcnt(0)
	v_mfma_f32_32x32x16_bf16 v[0:15], v[40:43], v[36:39], v[0:15]
	ds_read2_b64 v[40:43], v49 offset0:200 offset1:202
	s_waitcnt lgkmcnt(0)
	v_mfma_f32_32x32x16_bf16 v[16:31], v[40:43], v[36:39], v[16:31]
	ds_read2_b64 v[36:39], v58 offset0:140 offset1:142
	s_waitcnt lgkmcnt(0)
	v_mfma_f32_32x32x16_bf16 v[0:15], v[36:39], v[32:35], v[0:15]
	ds_read2_b64 v[36:39], v49 offset0:204 offset1:206
	s_waitcnt lgkmcnt(0)
	s_barrier
	v_mfma_f32_32x32x16_bf16 v[16:31], v[36:39], v[32:35], v[16:31]
	ds_read_b128 v[88:91], v94 offset:29344
	ds_read_b128 v[96:99], v94 offset:22688
	ds_read_b128 v[108:111], v94 offset:29312
	ds_read_b128 v[116:119], v94 offset:22656
	ds_read_b128 v[120:123], v94 offset:29280
	ds_read_b128 v[124:127], v94 offset:22624
	ds_read_b128 v[128:131], v94 offset:29248
	ds_read_b128 v[132:135], v94 offset:22592
	ds_read_b128 v[136:139], v94 offset:29216
	ds_read_b128 v[32:35], v94 offset:22528
	ds_read_b128 v[140:143], v94 offset:22560
	ds_read_b128 v[48:51], v94 offset:29184
	s_waitcnt lgkmcnt(2)
	v_mfma_f32_32x32x16_bf16 v[32:47], v[32:35], v[84:87], 0
	s_waitcnt lgkmcnt(0)
	v_mfma_f32_32x32x16_bf16 v[48:63], v[48:51], v[84:87], 0
	v_mfma_f32_32x32x16_bf16 v[32:47], v[140:143], v[80:83], v[32:47]
	v_mfma_f32_32x32x16_bf16 v[48:63], v[136:139], v[80:83], v[48:63]
	v_mfma_f32_32x32x16_bf16 v[32:47], v[132:135], v[76:79], v[32:47]
	v_mfma_f32_32x32x16_bf16 v[48:63], v[128:131], v[76:79], v[48:63]
	v_mfma_f32_32x32x16_bf16 v[32:47], v[124:127], v[72:75], v[32:47]
	v_mfma_f32_32x32x16_bf16 v[48:63], v[120:123], v[72:75], v[48:63]
	v_mfma_f32_32x32x16_bf16 v[32:47], v[116:119], v[68:71], v[32:47]
	v_mfma_f32_32x32x16_bf16 v[48:63], v[108:111], v[68:71], v[48:63]
	v_mfma_f32_32x32x16_bf16 v[32:47], v[96:99], v[64:67], v[32:47]
	v_mfma_f32_32x32x16_bf16 v[48:63], v[88:91], v[64:67], v[48:63]
	s_nop 10
	v_max_f32_e32 v65, v32, v32
	v_max_f32_e32 v64, v48, v48
	v_max_f32_e32 v64, v65, v64
	v_max3_f32 v64, v64, v33, v49
	v_max3_f32 v64, v64, v34, v50
	v_max3_f32 v64, v64, v35, v51
	v_max3_f32 v64, v64, v36, v52
	v_max3_f32 v64, v64, v37, v53
	v_max3_f32 v64, v64, v38, v54
	v_max3_f32 v64, v64, v39, v55
	v_max3_f32 v64, v64, v40, v56
	v_max3_f32 v64, v64, v41, v57
	v_max3_f32 v64, v64, v42, v58
	v_max3_f32 v64, v64, v43, v59
	v_max3_f32 v64, v64, v44, v60
	v_max3_f32 v64, v64, v45, v61
	v_max3_f32 v64, v64, v46, v62
	v_max3_f32 v64, v64, v47, v63
	v_cmp_gt_f32_e32 vcc, v64, v93
	s_cbranch_vccz .LBB0_650
	v_cmp_lt_i32_e32 vcc, v209, v208
	v_add_f32_e32 v64, 0, v64
	s_nop 0
	v_cndmask_b32_e32 v65, v207, v209, vcc
	v_lshlrev_b32_e32 v65, 2, v65
	ds_bpermute_b32 v65, v65, v64
	s_waitcnt lgkmcnt(0)
	v_max3_f32 v65, v107, v64, v65
	v_sub_f32_e32 v64, v107, v65
	v_exp_f32_e32 v64, v64
	v_sub_f32_e32 v104, 0, v65
	v_mov_b32_e32 v105, v104
	v_mul_f32_e32 v92, v92, v64
	v_pk_mul_f32 v[14:15], v[14:15], v[64:65] op_sel_hi:[1,0]
	v_pk_mul_f32 v[12:13], v[12:13], v[64:65] op_sel_hi:[1,0]
	v_pk_mul_f32 v[10:11], v[10:11], v[64:65] op_sel_hi:[1,0]
	v_pk_mul_f32 v[8:9], v[8:9], v[64:65] op_sel_hi:[1,0]
	v_pk_mul_f32 v[6:7], v[6:7], v[64:65] op_sel_hi:[1,0]
	v_pk_mul_f32 v[4:5], v[4:5], v[64:65] op_sel_hi:[1,0]
	v_pk_mul_f32 v[2:3], v[2:3], v[64:65] op_sel_hi:[1,0]
	v_pk_mul_f32 v[0:1], v[0:1], v[64:65] op_sel_hi:[1,0]
	v_pk_mul_f32 v[30:31], v[30:31], v[64:65] op_sel_hi:[1,0]
	v_pk_mul_f32 v[28:29], v[28:29], v[64:65] op_sel_hi:[1,0]
	v_pk_mul_f32 v[26:27], v[26:27], v[64:65] op_sel_hi:[1,0]
	v_pk_mul_f32 v[24:25], v[24:25], v[64:65] op_sel_hi:[1,0]
	v_pk_mul_f32 v[22:23], v[22:23], v[64:65] op_sel_hi:[1,0]
	v_pk_mul_f32 v[20:21], v[20:21], v[64:65] op_sel_hi:[1,0]
	v_pk_mul_f32 v[18:19], v[18:19], v[64:65] op_sel_hi:[1,0]
	v_pk_mul_f32 v[16:17], v[16:17], v[64:65] op_sel_hi:[1,0]

; DI f32x16 mfma32(bf16x8 a, bf16x8 b, f32x16 c) { return __builtin_amdgcn_mfma_f32_32x32x16_bf16(a, b, c, 0, 0, 0); }
; template <int MODE>
; DI void attn_unit(char* lds, const Params& p, int layer, int u) {
;     ...
;     if (t + 1 < NT) { stage(lds + ((t + 1) & 1) * BUFSZ); if (t + 2 < NT) prefetch(t + 2); }
;     const int key0 = (MODE == 3) ? q0 - 64 + 64 * t : 64 * (tlo + t);
;     const bool act = (MODE != 3) || (t >= (wid >> 1) && t <= (wid >> 1) + 2);
;     if (act) {
;       f32x16 S0 = zero16(), S1 = zero16();
;       const char* kb = cur + lr * KST + (MODE == 0 ? comp * 64 : 0) + lh * 16;
; #pragma unroll
;       for (int ks = 0; ks < NKS; ++ks) {
;         const bf16x8 k0 = *(const bf16x8*)(kb + ks * 32), k1 = *(const bf16x8*)(kb + 32 * KST + ks * 32);
;         S0 = mfma32(k0, qf[ks], S0); S1 = mfma32(k1, qf[ks], S1);
;       }
;       float aoff = 0.f;
;       if (MODE == 0) {
;         const float dbase = (float)(key0 + 4 * lh - qrow);
;         if (key0 > qlo + 31) { S0 = S0 - T0; S1 = S1 - T1; aoff = -slope2 * dbase; }
;         else if (key0 + 63 < qlo) { S0 = S0 + T0; S1 = S1 + T1; aoff = slope2 * dbase; }
;         else {
; #pragma unroll
;           for (int r = 0; r < 16; ++r) { const float cc = (float)((r & 3) + 8 * (r >> 2));
;             S0[r] = fmaf(-slope2, fabsf(dbase + cc), S0[r]); S1[r] = fmaf(-slope2, fabsf(dbase + cc + 32.f), S1[r]); }
;         }
;       }
;       if (MODE == 3) {
;         const int rel0 = key0 + 4 * lh - qrow;
; #pragma unroll
;         for (int r = 0; r < 16; ++r) { const int cc = (r & 3) + 8 * (r >> 2);
;           { const int rel = rel0 + cc, v = qrow + rel; const bool ok = (rel >= -64) && (rel <= 64) && (v >= 0) && (v < L); S0[r] = ok ? fmaf(-slope2, fabsf((float)rel), S0[r]) : -1e30f; }
;           { const int rel = rel0 + cc + 32, v = qrow + rel; const bool ok = (rel >= -64) && (rel <= 64) && (v >= 0) && (v < L); S1[r] = ok ? fmaf(-slope2, fabsf((float)rel), S1[r]) : -1e30f; } }
;       }
;       float mx = fmaxf(S0[0], S1[0]);
; #pragma unroll
;       for (int r = 1; r < 16; ++r) mx = max3f(mx, S0[r], S1[r]);
;       mx += aoff;
;       if (__any(mx > m + 8.f)) {
;         mx = fmaxf(mx, __shfl_xor(mx, 32));
;         const float mnew = fmaxf(m, mx);
;         const float al = __builtin_amdgcn_exp2f(m - mnew); l *= al; O0 *= al; O1 *= al;
;         m = mnew;
;       }
.LBB0_1577:
	s_or_b64 exec, exec, s[66:67]
	s_cmp_eq_u32 s50, 1
	s_cselect_b32 s50, 0, 0x5800
	v_add3_u32 v32, s51, v123, v108
	s_waitcnt vmcnt(0)
	ds_write_b128 v32, v[92:95] offset:13312
	v_add3_u32 v104, s50, v103, v106
	ds_read_b128 v[32:35], v104
	ds_read_b128 v[88:91], v104 offset:32
	ds_read_b128 v[48:51], v104 offset:6656
	v_readlane_b32 s8, v252, 0
	v_readlane_b32 s16, v252, 8
	v_readlane_b32 s17, v252, 9
	v_ashrrev_i32_e32 v117, 31, v116
	s_waitcnt lgkmcnt(2)
	v_mfma_f32_32x32x16_bf16 v[32:47], v[32:35], v[84:87], 0
	v_mov_b64_e32 v[92:93], s[16:17]
	v_mad_i64_i32 v[92:93], s[52:53], v116, s72, v[92:93]
	v_lshl_add_u64 v[92:93], v[92:93], 0, v[112:113]
	v_add_co_u32_e32 v92, vcc, s74, v92
	v_readlane_b32 s9, v252, 1
	s_waitcnt lgkmcnt(1)
	v_mfma_f32_32x32x16_bf16 v[32:47], v[88:91], v[80:83], v[32:47]
	ds_read_b128 v[88:91], v104 offset:6688
	v_addc_co_u32_e32 v93, vcc, 0, v93, vcc
	v_readlane_b32 s10, v252, 2
	v_readlane_b32 s11, v252, 3
	v_readlane_b32 s12, v252, 4
	v_readlane_b32 s13, v252, 5
	s_waitcnt lgkmcnt(1)
	v_mfma_f32_32x32x16_bf16 v[48:63], v[48:51], v[84:87], 0
	v_readlane_b32 s14, v252, 6
	v_readlane_b32 s15, v252, 7
	v_readlane_b32 s18, v252, 10
	v_readlane_b32 s19, v252, 11
	v_readlane_b32 s20, v252, 12
	v_readlane_b32 s21, v252, 13
	v_readlane_b32 s22, v252, 14
	s_waitcnt lgkmcnt(0)
	v_mfma_f32_32x32x16_bf16 v[48:63], v[88:91], v[80:83], v[48:63]
	ds_read_b128 v[88:91], v104 offset:64
	v_readlane_b32 s23, v252, 15
	s_waitcnt lgkmcnt(0)
	v_mfma_f32_32x32x16_bf16 v[32:47], v[88:91], v[76:79], v[32:47]
	ds_read_b128 v[88:91], v104 offset:6720
	ds_read_b128 v[126:129], v104 offset:96
	s_waitcnt lgkmcnt(1)
	v_mfma_f32_32x32x16_bf16 v[48:63], v[88:91], v[76:79], v[48:63]
	v_lshlrev_b64 v[88:89], 9, v[116:117]
	v_lshl_add_u64 v[88:89], v[110:111], 0, v[88:89]
	global_load_dwordx4 v[88:91], v[88:89], off
	s_nop 0
	global_load_dwordx4 v[96:99], v[92:93], off offset:1280
	s_nop 0
	global_load_dwordx4 v[92:95], v[118:119], off
	s_waitcnt lgkmcnt(0)
	v_mfma_f32_32x32x16_bf16 v[32:47], v[126:129], v[72:75], v[32:47]
	ds_read_b128 v[126:129], v104 offset:6752
	s_waitcnt lgkmcnt(0)
	v_mfma_f32_32x32x16_bf16 v[48:63], v[126:129], v[72:75], v[48:63]
	ds_read_b128 v[126:129], v104 offset:128
	s_waitcnt lgkmcnt(0)
	v_mfma_f32_32x32x16_bf16 v[32:47], v[126:129], v[68:71], v[32:47]
	ds_read_b128 v[126:129], v104 offset:6784
	s_waitcnt lgkmcnt(0)
	v_mfma_f32_32x32x16_bf16 v[48:63], v[126:129], v[68:71], v[48:63]
	ds_read_b128 v[126:129], v104 offset:6816
	s_waitcnt lgkmcnt(0)
	v_mfma_f32_32x32x16_bf16 v[48:63], v[126:129], v[64:67], v[48:63]
	ds_read_b128 v[126:129], v104 offset:160
	s_waitcnt lgkmcnt(0)
	v_mfma_f32_32x32x16_bf16 v[32:47], v[126:129], v[64:67], v[32:47]
	s_nop 8
	v_max_f32_e32 v104, v48, v48
	s_nop 1
	v_max_f32_e32 v105, v32, v32
	v_max_f32_e32 v104, v105, v104
	v_max3_f32 v104, v104, v33, v49
	v_add_f32_e32 v105, 0x41000000, v107
	v_max3_f32 v104, v104, v34, v50
	v_max3_f32 v104, v104, v35, v51
	v_max3_f32 v104, v104, v36, v52
	v_max3_f32 v104, v104, v37, v53
	v_max3_f32 v104, v104, v38, v54
	v_max3_f32 v104, v104, v39, v55
	v_max3_f32 v104, v104, v40, v56
	v_max3_f32 v104, v104, v41, v57
	v_max3_f32 v104, v104, v42, v58
	v_max3_f32 v104, v104, v43, v59
	v_max3_f32 v104, v104, v44, v60
	v_max3_f32 v104, v104, v45, v61
	v_max3_f32 v104, v104, v46, v62
	v_max3_f32 v104, v104, v47, v63
	v_cmp_gt_f32_e32 vcc, v104, v105
	s_cbranch_vccz .LBB0_1574
	v_cmp_lt_i32_e32 vcc, v209, v208
	v_add_f32_e32 v104, 0, v104
	s_nop 0
	v_cndmask_b32_e32 v105, v207, v209, vcc
	v_lshlrev_b32_e32 v105, 2, v105
	ds_bpermute_b32 v105, v105, v104
	s_waitcnt lgkmcnt(0)
	v_max3_f32 v105, v107, v104, v105
	v_sub_f32_e32 v104, v107, v105
	v_exp_f32_e32 v104, v104
	v_mov_b32_e32 v107, v105
	v_mul_f32_e32 v109, v109, v104
	v_pk_mul_f32 v[14:15], v[14:15], v[104:105] op_sel_hi:[1,0]
	v_pk_mul_f32 v[12:13], v[12:13], v[104:105] op_sel_hi:[1,0]
	v_pk_mul_f32 v[10:11], v[10:11], v[104:105] op_sel_hi:[1,0]
	v_pk_mul_f32 v[8:9], v[8:9], v[104:105] op_sel_hi:[1,0]
	v_pk_mul_f32 v[6:7], v[6:7], v[104:105] op_sel_hi:[1,0]
	v_pk_mul_f32 v[4:5], v[4:5], v[104:105] op_sel_hi:[1,0]
	v_pk_mul_f32 v[2:3], v[2:3], v[104:105] op_sel_hi:[1,0]
	v_pk_mul_f32 v[0:1], v[0:1], v[104:105] op_sel_hi:[1,0]
	v_pk_mul_f32 v[30:31], v[30:31], v[104:105] op_sel_hi:[1,0]
	v_pk_mul_f32 v[28:29], v[28:29], v[104:105] op_sel_hi:[1,0]
	v_pk_mul_f32 v[26:27], v[26:27], v[104:105] op_sel_hi:[1,0]
	v_pk_mul_f32 v[24:25], v[24:25], v[104:105] op_sel_hi:[1,0]
	v_pk_mul_f32 v[22:23], v[22:23], v[104:105] op_sel_hi:[1,0]
	v_pk_mul_f32 v[20:21], v[20:21], v[104:105] op_sel_hi:[1,0]
	v_pk_mul_f32 v[18:19], v[18:19], v[104:105] op_sel_hi:[1,0]
	v_pk_mul_f32 v[16:17], v[16:17], v[104:105] op_sel_hi:[1,0]
	s_branch .LBB0_1574
